# grid barrier spin loops poll with s_sleep 0 instead of s_sleep 1
# speedup vs baseline: 1.0087x; 1.0087x over previous
; __device__ __forceinline__ unsigned xb_ld(unsigned* p)              { return __hip_atomic_load(p, __ATOMIC_RELAXED, __HIP_MEMORY_SCOPE_AGENT); }
; __device__ __forceinline__ void xcd_barrier_complete(unsigned* bar, unsigned x, unsigned& nloc, unsigned& nx) {
;     const unsigned G = gridDim.x * gridDim.y * gridDim.z;
;     unsigned sum, cnt, mine, sp = 0u;
;     for (;;) {
;         sum = 0u; cnt = 0u; mine = 0u;
; #pragma unroll
;         for (unsigned j = 0; j < 16; ++j) { const unsigned c = xb_ld(&bar[XB_XCNT(j)]); sum += c; cnt += (c > 0u) ? 1u : 0u; mine = (j == x) ? c : mine; }
;         if (sum == G) break;
;         __builtin_amdgcn_s_sleep(1);
;         if ((++sp & 255u) == 0u) { if (xb_ld(&bar[XB_TMO])) break; if (sp > XB_SPIN_CAP) { atomicAdd(&bar[XB_TMO], 1u); break; } }
;     }
.LBB0_151:
	v_readlane_b32 s6, v252, 18
	v_readlane_b32 s7, v252, 19
	global_load_dword v4, v0, s[58:59] sc1
	s_waitcnt lgkmcnt(0)
	global_load_dword v1, v0, s[62:63] sc1
	global_load_dword v2, v0, s[56:57] sc1
	global_load_dword v3, v0, s[42:43] sc1
	s_mov_b64 s[8:9], -1
	global_load_dword v5, v0, s[6:7] sc1
	v_readlane_b32 s6, v252, 20
	v_readlane_b32 s7, v252, 21
	s_waitcnt vmcnt(3)
	v_add_u32_e32 v18, v1, v4
	s_nop 2
	global_load_dword v6, v0, s[6:7] sc1
	v_readlane_b32 s6, v252, 22
	v_readlane_b32 s7, v252, 23
	s_waitcnt vmcnt(3)
	v_add_u32_e32 v18, v18, v2
	s_waitcnt vmcnt(2)
	v_add_u32_e32 v18, v18, v3
	s_waitcnt vmcnt(1)
	v_add_u32_e32 v18, v18, v5
	s_waitcnt vmcnt(0)
	v_add_u32_e32 v18, v18, v6
	global_load_dword v7, v0, s[6:7] sc1
	v_readlane_b32 s6, v252, 24
	v_readlane_b32 s7, v252, 25
	s_nop 4
	global_load_dword v8, v0, s[6:7] sc1
	global_load_dword v9, v0, s[92:93] sc1
	global_load_dword v10, v0, s[94:95] sc1
	global_load_dword v11, v0, s[96:97] sc1
	global_load_dword v12, v0, s[98:99] sc1
	global_load_dword v13, v0, s[64:65] sc1
	v_readlane_b32 s6, v252, 26
	v_readlane_b32 s7, v252, 27
	s_waitcnt vmcnt(6)
	v_add_u32_e32 v18, v18, v7
	s_nop 2
	global_load_dword v14, v0, s[6:7] sc1
	v_readlane_b32 s6, v252, 28
	v_readlane_b32 s7, v252, 29
	s_waitcnt vmcnt(6)
	v_add_u32_e32 v18, v18, v8
	s_waitcnt vmcnt(5)
	v_add_u32_e32 v18, v18, v9
	s_waitcnt vmcnt(4)
	v_add_u32_e32 v18, v18, v10
	s_waitcnt vmcnt(3)
	v_add_u32_e32 v18, v18, v11
	s_waitcnt vmcnt(2)
	v_add_u32_e32 v18, v18, v12
	global_load_dword v15, v0, s[6:7] sc1
	v_readlane_b32 s6, v252, 30
	v_readlane_b32 s7, v252, 31
	s_waitcnt vmcnt(2)
	v_add_u32_e32 v18, v18, v13
	s_waitcnt vmcnt(1)
	v_add_u32_e32 v18, v18, v14
	s_nop 0
	global_load_dword v17, v0, s[6:7] sc1
	s_mov_b64 s[6:7], -1
	s_waitcnt vmcnt(1)
	v_add_u32_e32 v18, v18, v15
	s_waitcnt vmcnt(0)
	v_add_u32_e32 v18, v18, v17
	v_cmp_eq_u32_e32 vcc, s66, v18
	s_cbranch_vccnz .LBB0_150
	s_and_b32 s1, s0, 0xff
	s_cmp_eq_u32 s1, 0
	s_mov_b64 s[10:11], -1
	s_sleep 0
	s_cbranch_scc0 .LBB0_155
	v_readlane_b32 s6, v252, 16
	v_readlane_b32 s7, v252, 17
	s_nop 4
	global_load_dword v18, v0, s[6:7] sc1
	s_waitcnt vmcnt(0)
	v_cmp_eq_u32_e32 vcc, 0, v18
	s_cbranch_vccnz .LBB0_157
	s_mov_b64 s[10:11], 0
	s_mov_b64 s[6:7], -1

; __device__ __forceinline__ unsigned xb_ld(unsigned* p)              { return __hip_atomic_load(p, __ATOMIC_RELAXED, __HIP_MEMORY_SCOPE_AGENT); }
; __device__ __forceinline__ unsigned xb_add(unsigned* p, unsigned v) { return __hip_atomic_fetch_add(p, v, __ATOMIC_RELAXED, __HIP_MEMORY_SCOPE_AGENT); }
; #define XB_SPIN(cond, bar) do { unsigned _sp = 0; while (cond) { __builtin_amdgcn_s_sleep(1); \
;     if ((++_sp & 255u) == 0u) { if (xb_ld(&(bar)[XB_TMO])) break; if (_sp > XB_SPIN_CAP) { atomicAdd(&(bar)[XB_TMO], 1u); break; } } } } while (0)
; __device__ __forceinline__ void xcd_barrier(const XcdBarrier& b) {
;     ...
;             else XB_SPIN(xb_ld(&bar[XB_TOPGEN]) == tg, bar);
;             __builtin_amdgcn_fence(__ATOMIC_ACQUIRE, "agent");
;             xb_add(&bar[XB_XGEN(b.x)], 1u);
;             asm volatile("s_waitcnt vmcnt(0)" ::: "memory");
;         } else {
;             XB_SPIN(xb_ld(&bar[XB_XGEN(b.x)]) == gen, bar);
.LBB0_170:
	s_and_b32 s1, s0, 0xff
	s_mov_b64 s[14:15], -1
	s_cmp_lg_u32 s1, 0
	s_mov_b64 s[20:21], -1
	s_sleep 0
	s_cbranch_scc1 .LBB0_173
	v_readlane_b32 s18, v252, 16
	v_readlane_b32 s19, v252, 17
	s_nop 4
	global_load_dword v1, v0, s[18:19] sc1
	s_waitcnt vmcnt(0)
	v_cmp_eq_u32_e32 vcc, 0, v1
	s_cbranch_vccnz .LBB0_175
	s_mov_b64 s[20:21], 0
	s_mov_b64 s[18:19], -1

; __global__ void __launch_bounds__(512, 2) hymba_fwd(Args a) {
;     ...
;         if (layer == 0) grid.sync(); else xcd_barrier(bar);
.LBB0_209:
	s_sleep 0
	global_load_dword v2, v0, s[6:7] offset:32 sc1
	s_waitcnt vmcnt(0)
	v_and_b32_e32 v2, 0xffff0000, v2
	v_cmp_ne_u32_e32 vcc, v2, v1
	s_or_b64 s[8:9], vcc, s[8:9]
	s_andn2_b64 exec, exec, s[8:9]
	s_cbranch_execnz .LBB0_209

; __device__ __forceinline__ unsigned xb_ld(unsigned* p)              { return __hip_atomic_load(p, __ATOMIC_RELAXED, __HIP_MEMORY_SCOPE_AGENT); }
; __device__ __forceinline__ void xcd_barrier_complete(unsigned* bar, unsigned x, unsigned& nloc, unsigned& nx) {
;     const unsigned G = gridDim.x * gridDim.y * gridDim.z;
;     unsigned sum, cnt, mine, sp = 0u;
;     for (;;) {
;         sum = 0u; cnt = 0u; mine = 0u;
; #pragma unroll
;         for (unsigned j = 0; j < 16; ++j) { const unsigned c = xb_ld(&bar[XB_XCNT(j)]); sum += c; cnt += (c > 0u) ? 1u : 0u; mine = (j == x) ? c : mine; }
;         if (sum == G) break;
;         __builtin_amdgcn_s_sleep(1);
;         if ((++sp & 255u) == 0u) { if (xb_ld(&bar[XB_TMO])) break; if (sp > XB_SPIN_CAP) { atomicAdd(&bar[XB_TMO], 1u); break; } }
;     }
.LBB0_423:
	v_readlane_b32 s4, v252, 18
	v_readlane_b32 s5, v252, 19
	global_load_dword v4, v0, s[58:59] sc1
	global_load_dword v1, v0, s[62:63] sc1
	s_waitcnt lgkmcnt(0)
	global_load_dword v2, v0, s[56:57] sc1
	global_load_dword v3, v0, s[42:43] sc1
	s_mov_b64 s[6:7], -1
	global_load_dword v5, v0, s[4:5] sc1
	v_readlane_b32 s4, v252, 20
	v_readlane_b32 s5, v252, 21
	s_waitcnt vmcnt(3)
	v_add_u32_e32 v18, v1, v4
	s_nop 2
	global_load_dword v6, v0, s[4:5] sc1
	v_readlane_b32 s4, v252, 22
	v_readlane_b32 s5, v252, 23
	s_waitcnt vmcnt(3)
	v_add_u32_e32 v18, v18, v2
	s_waitcnt vmcnt(2)
	v_add_u32_e32 v18, v18, v3
	s_waitcnt vmcnt(1)
	v_add_u32_e32 v18, v18, v5
	s_waitcnt vmcnt(0)
	v_add_u32_e32 v18, v18, v6
	global_load_dword v7, v0, s[4:5] sc1
	v_readlane_b32 s4, v252, 24
	v_readlane_b32 s5, v252, 25
	s_nop 4
	global_load_dword v8, v0, s[4:5] sc1
	global_load_dword v9, v0, s[92:93] sc1
	global_load_dword v10, v0, s[94:95] sc1
	global_load_dword v11, v0, s[96:97] sc1
	global_load_dword v12, v0, s[98:99] sc1
	global_load_dword v13, v0, s[64:65] sc1
	v_readlane_b32 s4, v252, 26
	v_readlane_b32 s5, v252, 27
	s_waitcnt vmcnt(6)
	v_add_u32_e32 v18, v18, v7
	s_nop 2
	global_load_dword v14, v0, s[4:5] sc1
	v_readlane_b32 s4, v252, 28
	v_readlane_b32 s5, v252, 29
	s_waitcnt vmcnt(6)
	v_add_u32_e32 v18, v18, v8
	s_waitcnt vmcnt(5)
	v_add_u32_e32 v18, v18, v9
	s_waitcnt vmcnt(4)
	v_add_u32_e32 v18, v18, v10
	s_waitcnt vmcnt(3)
	v_add_u32_e32 v18, v18, v11
	s_waitcnt vmcnt(2)
	v_add_u32_e32 v18, v18, v12
	global_load_dword v15, v0, s[4:5] sc1
	v_readlane_b32 s4, v252, 30
	v_readlane_b32 s5, v252, 31
	s_waitcnt vmcnt(2)
	v_add_u32_e32 v18, v18, v13
	s_waitcnt vmcnt(1)
	v_add_u32_e32 v18, v18, v14
	s_nop 0
	global_load_dword v17, v0, s[4:5] sc1
	s_mov_b64 s[4:5], -1
	s_waitcnt vmcnt(1)
	v_add_u32_e32 v18, v18, v15
	s_waitcnt vmcnt(0)
	v_add_u32_e32 v18, v18, v17
	v_cmp_eq_u32_e32 vcc, s66, v18
	s_cbranch_vccnz .LBB0_422
	s_and_b32 s1, s0, 0xff
	s_cmp_eq_u32 s1, 0
	s_mov_b64 s[12:13], -1
	s_sleep 0
	s_cbranch_scc0 .LBB0_427
	v_readlane_b32 s4, v252, 16
	v_readlane_b32 s5, v252, 17
	s_nop 4
	global_load_dword v18, v0, s[4:5] sc1
	s_waitcnt vmcnt(0)
	v_cmp_eq_u32_e32 vcc, 0, v18
	s_cbranch_vccnz .LBB0_429
	s_mov_b64 s[12:13], 0
	s_mov_b64 s[4:5], -1

; __device__ __forceinline__ unsigned xb_ld(unsigned* p)              { return __hip_atomic_load(p, __ATOMIC_RELAXED, __HIP_MEMORY_SCOPE_AGENT); }
; __device__ __forceinline__ unsigned xb_add(unsigned* p, unsigned v) { return __hip_atomic_fetch_add(p, v, __ATOMIC_RELAXED, __HIP_MEMORY_SCOPE_AGENT); }
; #define XB_SPIN(cond, bar) do { unsigned _sp = 0; while (cond) { __builtin_amdgcn_s_sleep(1); \
;     if ((++_sp & 255u) == 0u) { if (xb_ld(&(bar)[XB_TMO])) break; if (_sp > XB_SPIN_CAP) { atomicAdd(&(bar)[XB_TMO], 1u); break; } } } } while (0)
; __device__ __forceinline__ void xcd_barrier(const XcdBarrier& b) {
;     ...
;             else XB_SPIN(xb_ld(&bar[XB_TOPGEN]) == tg, bar);
;             __builtin_amdgcn_fence(__ATOMIC_ACQUIRE, "agent");
;             xb_add(&bar[XB_XGEN(b.x)], 1u);
;             asm volatile("s_waitcnt vmcnt(0)" ::: "memory");
;         } else {
;             XB_SPIN(xb_ld(&bar[XB_XGEN(b.x)]) == gen, bar);
.LBB0_441:
	s_and_b32 s1, s0, 0xff
	s_mov_b64 s[18:19], -1
	s_cmp_lg_u32 s1, 0
	s_mov_b64 s[24:25], -1
	s_sleep 0
	s_cbranch_scc1 .LBB0_444
	v_readlane_b32 s20, v252, 16
	v_readlane_b32 s21, v252, 17
	s_nop 4
	global_load_dword v2, v0, s[20:21] sc1
	s_waitcnt vmcnt(0)
	v_cmp_eq_u32_e32 vcc, 0, v2
	s_cbranch_vccnz .LBB0_446
	s_mov_b64 s[24:25], 0
	s_mov_b64 s[20:21], -1

; __device__ __forceinline__ unsigned xb_ld(unsigned* p)              { return __hip_atomic_load(p, __ATOMIC_RELAXED, __HIP_MEMORY_SCOPE_AGENT); }
; __device__ __forceinline__ void xcd_barrier_complete(unsigned* bar, unsigned x, unsigned& nloc, unsigned& nx) {
;     const unsigned G = gridDim.x * gridDim.y * gridDim.z;
;     unsigned sum, cnt, mine, sp = 0u;
;     for (;;) {
;         sum = 0u; cnt = 0u; mine = 0u;
; #pragma unroll
;         for (unsigned j = 0; j < 16; ++j) { const unsigned c = xb_ld(&bar[XB_XCNT(j)]); sum += c; cnt += (c > 0u) ? 1u : 0u; mine = (j == x) ? c : mine; }
;         if (sum == G) break;
;         __builtin_amdgcn_s_sleep(1);
;         if ((++sp & 255u) == 0u) { if (xb_ld(&bar[XB_TMO])) break; if (sp > XB_SPIN_CAP) { atomicAdd(&bar[XB_TMO], 1u); break; } }
;     }
.LBB0_601:
	v_readlane_b32 s4, v252, 18
	v_readlane_b32 s5, v252, 19
	global_load_dword v4, v0, s[58:59] sc1
	global_load_dword v1, v0, s[62:63] sc1
	s_waitcnt lgkmcnt(0)
	global_load_dword v2, v0, s[56:57] sc1
	global_load_dword v3, v0, s[42:43] sc1
	s_mov_b64 s[6:7], -1
	global_load_dword v5, v0, s[4:5] sc1
	v_readlane_b32 s4, v252, 20
	v_readlane_b32 s5, v252, 21
	s_waitcnt vmcnt(3)
	v_add_u32_e32 v18, v1, v4
	s_nop 2
	global_load_dword v6, v0, s[4:5] sc1
	v_readlane_b32 s4, v252, 22
	v_readlane_b32 s5, v252, 23
	s_waitcnt vmcnt(3)
	v_add_u32_e32 v18, v18, v2
	s_waitcnt vmcnt(2)
	v_add_u32_e32 v18, v18, v3
	s_waitcnt vmcnt(1)
	v_add_u32_e32 v18, v18, v5
	s_waitcnt vmcnt(0)
	v_add_u32_e32 v18, v18, v6
	global_load_dword v7, v0, s[4:5] sc1
	v_readlane_b32 s4, v252, 24
	v_readlane_b32 s5, v252, 25
	s_nop 4
	global_load_dword v8, v0, s[4:5] sc1
	global_load_dword v9, v0, s[92:93] sc1
	global_load_dword v10, v0, s[94:95] sc1
	global_load_dword v11, v0, s[96:97] sc1
	global_load_dword v12, v0, s[98:99] sc1
	global_load_dword v13, v0, s[64:65] sc1
	v_readlane_b32 s4, v252, 26
	v_readlane_b32 s5, v252, 27
	s_waitcnt vmcnt(6)
	v_add_u32_e32 v18, v18, v7
	s_nop 2
	global_load_dword v14, v0, s[4:5] sc1
	v_readlane_b32 s4, v252, 28
	v_readlane_b32 s5, v252, 29
	s_waitcnt vmcnt(6)
	v_add_u32_e32 v18, v18, v8
	s_waitcnt vmcnt(5)
	v_add_u32_e32 v18, v18, v9
	s_waitcnt vmcnt(4)
	v_add_u32_e32 v18, v18, v10
	s_waitcnt vmcnt(3)
	v_add_u32_e32 v18, v18, v11
	s_waitcnt vmcnt(2)
	v_add_u32_e32 v18, v18, v12
	global_load_dword v15, v0, s[4:5] sc1
	v_readlane_b32 s4, v252, 30
	v_readlane_b32 s5, v252, 31
	s_waitcnt vmcnt(2)
	v_add_u32_e32 v18, v18, v13
	s_waitcnt vmcnt(1)
	v_add_u32_e32 v18, v18, v14
	s_nop 0
	global_load_dword v17, v0, s[4:5] sc1
	s_mov_b64 s[4:5], -1
	s_waitcnt vmcnt(1)
	v_add_u32_e32 v18, v18, v15
	s_waitcnt vmcnt(0)
	v_add_u32_e32 v18, v18, v17
	v_cmp_eq_u32_e32 vcc, s66, v18
	s_cbranch_vccnz .LBB0_600
	s_and_b32 s1, s0, 0xff
	s_cmp_eq_u32 s1, 0
	s_mov_b64 s[8:9], -1
	s_sleep 0
	s_cbranch_scc0 .LBB0_605
	v_readlane_b32 s4, v252, 16
	v_readlane_b32 s5, v252, 17
	s_nop 4
	global_load_dword v18, v0, s[4:5] sc1
	s_waitcnt vmcnt(0)
	v_cmp_eq_u32_e32 vcc, 0, v18
	s_cbranch_vccnz .LBB0_607
	s_mov_b64 s[8:9], 0
	s_mov_b64 s[4:5], -1

; __device__ __forceinline__ unsigned xb_ld(unsigned* p)              { return __hip_atomic_load(p, __ATOMIC_RELAXED, __HIP_MEMORY_SCOPE_AGENT); }
; __device__ __forceinline__ unsigned xb_add(unsigned* p, unsigned v) { return __hip_atomic_fetch_add(p, v, __ATOMIC_RELAXED, __HIP_MEMORY_SCOPE_AGENT); }
; #define XB_SPIN(cond, bar) do { unsigned _sp = 0; while (cond) { __builtin_amdgcn_s_sleep(1); \
;     if ((++_sp & 255u) == 0u) { if (xb_ld(&(bar)[XB_TMO])) break; if (_sp > XB_SPIN_CAP) { atomicAdd(&(bar)[XB_TMO], 1u); break; } } } } while (0)
; __device__ __forceinline__ void xcd_barrier(const XcdBarrier& b) {
;     ...
;             else XB_SPIN(xb_ld(&bar[XB_TOPGEN]) == tg, bar);
;             __builtin_amdgcn_fence(__ATOMIC_ACQUIRE, "agent");
;             xb_add(&bar[XB_XGEN(b.x)], 1u);
;             asm volatile("s_waitcnt vmcnt(0)" ::: "memory");
;         } else {
;             XB_SPIN(xb_ld(&bar[XB_XGEN(b.x)]) == gen, bar);
.LBB0_619:
	s_and_b32 s1, s0, 0xff
	s_mov_b64 s[12:13], -1
	s_cmp_lg_u32 s1, 0
	s_mov_b64 s[18:19], -1
	s_sleep 0
	s_cbranch_scc1 .LBB0_622
	v_readlane_b32 s14, v252, 16
	v_readlane_b32 s15, v252, 17
	s_nop 4
	global_load_dword v2, v0, s[14:15] sc1
	s_waitcnt vmcnt(0)
	v_cmp_eq_u32_e32 vcc, 0, v2
	s_cbranch_vccnz .LBB0_624
	s_mov_b64 s[18:19], 0
	s_mov_b64 s[14:15], -1
